# ffnconv: row-load addresses from scalar base + 32-bit lane offset (SALU) instead of per-load 64-bit VALU multiply-add
# speedup vs baseline: 1.0117x; 1.0071x over previous
.LBB0_1256:
	s_movk_i32 s4, 0x2bf
	v_cmp_lt_i32_e32 vcc, s4, v95
	v_add_lshl_u32 v48, v95, s24, 1
	s_and_saveexec_b64 s[4:5], vcc
	s_xor_b64 s[6:7], exec, s[4:5]
	s_cbranch_execz .LBB0_1271
	v_add_u32_e32 v2, 0xfffffa80, v48
	v_readlane_b32 s4, v232, 17
	v_lshlrev_b64 v[20:21], 2, v[2:3]
	v_readlane_b32 s5, v232, 18
	v_lshl_add_u64 v[22:23], s[14:15], 0, v[20:21]
	v_lshl_add_u64 v[24:25], s[26:27], 0, v[20:21]
	v_lshl_add_u64 v[8:9], s[4:5], 0, v[20:21]
	v_readlane_b32 s4, v232, 19
	v_add_co_u32_e32 v10, vcc, 0x5000, v8
	v_readlane_b32 s5, v232, 20
	s_nop 0
	v_addc_co_u32_e32 v11, vcc, 0, v9, vcc
	v_lshl_add_u64 v[12:13], s[4:5], 0, v[20:21]
	v_readlane_b32 s4, v232, 21
	v_add_co_u32_e32 v14, vcc, 0x5000, v12
	v_readlane_b32 s5, v232, 22
	s_nop 0
	v_addc_co_u32_e32 v15, vcc, 0, v13, vcc
	v_lshl_add_u64 v[16:17], s[4:5], 0, v[20:21]
	global_load_dwordx2 v[8:9], v[8:9], off
	s_nop 0
	global_load_dwordx2 v[10:11], v[10:11], off offset:2048
	s_nop 0
	global_load_dwordx2 v[12:13], v[12:13], off
	s_nop 0
	global_load_dwordx2 v[14:15], v[14:15], off offset:2048
	v_add_co_u32_e32 v18, vcc, 0x5000, v16
	v_readlane_b32 s4, v232, 25
	s_nop 0
	v_addc_co_u32_e32 v19, vcc, 0, v17, vcc
	global_load_dwordx2 v[16:17], v[16:17], off
	s_nop 0
	global_load_dwordx2 v[18:19], v[18:19], off offset:2048
	s_nop 0
	global_load_dwordx2 v[20:21], v[22:23], off
	s_nop 0
	global_load_dwordx2 v[22:23], v[24:25], off
	v_readlane_b32 s5, v232, 26
	s_andn2_b64 vcc, exec, s[4:5]
	v_lshlrev_b32_e32 v160, 1, v2
	v_add_u32_e32 v161, 0x2c00, v160
	v_lshl_add_u64 v[24:25], v[2:3], 1, s[10:11]
	s_cbranch_vccnz .LBB0_1259
	v_readlane_b32 s4, v232, 27
	v_readlane_b32 s5, v232, 28
	s_nop 1
	v_lshl_add_u64 v[26:27], v[24:25], 0, s[4:5]
	v_add_co_u32_e32 v28, vcc, 0x2000, v26
	s_nop 1
	v_addc_co_u32_e32 v29, vcc, 0, v27, vcc
	global_load_dword v30, v[26:27], off nt
	global_load_dword v31, v[28:29], off offset:3072 nt
	s_branch .LBB0_1260

.LBB0_1262:
	s_waitcnt vmcnt(8)
	v_mov_b32_e32 v51, v47
	v_mov_b32_e32 v52, v61
	v_mov_b32_e32 v53, v66
	v_mov_b32_e32 v54, v63
	v_mov_b32_e32 v58, v2
	v_mov_b32_e32 v59, v57
	v_mov_b32_e32 v60, v65
	s_cmp_eq_u32 s4, 28
	v_mov_b32_e32 v62, v67
	s_cbranch_scc1 .LBB0_1261
	v_lshl_add_u64 v[28:29], s[8:9], 0, v[26:27]
	v_add_co_u32_e32 v46, vcc, 0x15933000, v28
	s_add_i32 s5, s18, s4
	s_nop 0
	v_addc_co_u32_e32 v47, vcc, 0, v29, vcc
	v_add_co_u32_e32 v48, vcc, 0x15936000, v28
	s_add_i32 s5, s5, 5
	s_nop 0
	v_addc_co_u32_e32 v49, vcc, 0, v29, vcc
	global_load_dword v5, v[46:47], off offset:2048 nt
	global_load_dword v7, v[48:49], off offset:1024 nt
	v_mov_b32_e32 v46, 0
	s_cmpk_gt_u32 s5, 0xdf
	v_mov_b32_e32 v49, 0
	v_mov_b32_e32 v50, 0
	s_cbranch_scc1 .LBB0_1265
	s_add_i32 s25, s19, s4
	s_add_i32 s25, s25, 37
	s_mul_i32 s98, s25, 0x5800
	s_add_u32 s98, s98, s10
	s_addc_u32 s99, s11, 0
	global_load_dword v49, v160, s[98:99] nt
	s_nop 0
	global_load_dword v50, v161, s[98:99] nt
.LBB0_1265:
	v_add_co_u32_e32 v56, vcc, 0x15939000, v28
	s_cmpk_gt_u32 s5, 0xde
	s_nop 0
	v_addc_co_u32_e32 v57, vcc, 0, v29, vcc
	v_add_co_u32_e32 v64, vcc, 0x1593b000, v28
	s_nop 1
	v_addc_co_u32_e32 v65, vcc, 0, v29, vcc
	global_load_dword v55, v[56:57], off nt
	s_nop 0
	global_load_dword v56, v[64:65], off offset:3072 nt
	v_mov_b32_e32 v64, 0
	s_cbranch_scc1 .LBB0_1267
	s_add_i32 s25, s19, s4
	s_add_i32 s25, s25, 38
	s_mul_i32 s98, s25, 0x5800
	s_add_u32 s98, s98, s10
	s_addc_u32 s99, s11, 0
	global_load_dword v46, v160, s[98:99] nt
	s_nop 0
	global_load_dword v64, v161, s[98:99] nt
.LBB0_1267:
	v_add_co_u32_e32 v66, vcc, 0x1593e000, v28
	v_mov_b32_e32 v63, 0
	s_nop 0
	v_addc_co_u32_e32 v67, vcc, 0, v29, vcc
	v_add_co_u32_e32 v68, vcc, 0x15941000, v28
	s_cmpk_gt_u32 s5, 0xdd
	s_nop 0
	v_addc_co_u32_e32 v69, vcc, 0, v29, vcc
	global_load_dword v2, v[66:67], off offset:2048 nt
	global_load_dword v47, v[68:69], off offset:1024 nt
	v_mov_b32_e32 v57, 0
	v_mov_b32_e32 v61, 0
	s_cbranch_scc1 .LBB0_1269
	s_add_i32 s25, s19, s4
	s_add_i32 s25, s25, 39
	s_mul_i32 s98, s25, 0x5800
	s_add_u32 s98, s98, s10
	s_addc_u32 s99, s11, 0
	global_load_dword v57, v160, s[98:99] nt
	global_load_dword v61, v161, s[98:99] nt
.LBB0_1269:
	v_add_co_u32_e32 v66, vcc, 0x15944000, v28
	s_cmpk_gt_u32 s5, 0xdc
	s_nop 0
	v_addc_co_u32_e32 v67, vcc, 0, v29, vcc
	v_add_co_u32_e32 v28, vcc, 0x15946000, v28
	s_nop 1
	v_addc_co_u32_e32 v29, vcc, 0, v29, vcc
	global_load_dword v65, v[66:67], off nt
	s_nop 0
	global_load_dword v66, v[28:29], off offset:3072 nt
	v_mov_b32_e32 v67, 0
	s_cbranch_scc1 .LBB0_1261
	s_add_i32 s5, s19, s4
	s_add_i32 s5, s5, 40
	s_mul_i32 s98, s5, 0x5800
	s_add_u32 s98, s98, s10
	s_addc_u32 s99, s11, 0
	global_load_dword v67, v160, s[98:99] nt
	global_load_dword v63, v161, s[98:99] nt
	s_branch .LBB0_1261
.LBB0_1271:
	s_andn2_saveexec_b64 s[16:17], s[6:7]
	s_cbranch_execz .LBB0_1255
	v_ashrrev_i32_e32 v49, 31, v48
	v_lshlrev_b64 v[44:45], 2, v[48:49]
	v_lshl_add_u64 v[40:41], s[12:13], 0, v[44:45]
	v_add_co_u32_e32 v10, vcc, 0x5000, v40
	v_lshl_add_u64 v[50:51], s[26:27], 0, v[44:45]
	s_nop 0
	v_addc_co_u32_e32 v11, vcc, 0, v41, vcc
	v_add_co_u32_e32 v12, vcc, 0xb000, v40
	v_lshlrev_b32_e32 v162, 1, v48
	v_add_u32_e32 v163, 0x2c00, v162
	v_lshl_add_u64 v[48:49], v[48:49], 1, s[10:11]
	s_nop 0
	v_addc_co_u32_e32 v13, vcc, 0, v41, vcc
	v_add_co_u32_e32 v14, vcc, 0x10000, v40
	v_mov_b32_e32 v52, 0
	s_nop 0
	v_addc_co_u32_e32 v15, vcc, 0, v41, vcc
	v_add_co_u32_e32 v16, vcc, 0x16000, v40
	global_load_dwordx2 v[8:9], v[40:41], off
	s_nop 0
	global_load_dwordx2 v[10:11], v[10:11], off offset:2048
	s_nop 0
	global_load_dwordx2 v[12:13], v[12:13], off
	s_nop 0
	global_load_dwordx2 v[14:15], v[14:15], off offset:2048
	v_addc_co_u32_e32 v17, vcc, 0, v41, vcc
	v_add_co_u32_e32 v18, vcc, 0x1b000, v40
	v_mov_b32_e32 v53, 0
	s_nop 0
	v_addc_co_u32_e32 v19, vcc, 0, v41, vcc
	v_add_co_u32_e32 v20, vcc, 0x21000, v40
	s_waitcnt vmcnt(15)
	v_mov_b32_e32 v57, 0
	v_addc_co_u32_e32 v21, vcc, 0, v41, vcc
	v_add_co_u32_e32 v22, vcc, 0x26000, v40
	s_nop 1
	v_addc_co_u32_e32 v23, vcc, 0, v41, vcc
	v_add_co_u32_e32 v24, vcc, 0x2c000, v40
	global_load_dwordx2 v[16:17], v[16:17], off
	s_nop 0
	global_load_dwordx2 v[18:19], v[18:19], off offset:2048
	s_nop 0
	global_load_dwordx2 v[20:21], v[20:21], off
	s_nop 0
	global_load_dwordx2 v[22:23], v[22:23], off offset:2048
	v_addc_co_u32_e32 v25, vcc, 0, v41, vcc
	v_add_co_u32_e32 v26, vcc, 0x31000, v40
	s_nop 1
	v_addc_co_u32_e32 v27, vcc, 0, v41, vcc
	v_add_co_u32_e32 v28, vcc, 0x37000, v40
	s_nop 1
	v_addc_co_u32_e32 v29, vcc, 0, v41, vcc
	v_add_co_u32_e32 v30, vcc, 0x3c000, v40
	s_nop 1
	v_addc_co_u32_e32 v31, vcc, 0, v41, vcc
	v_add_co_u32_e32 v32, vcc, 0x42000, v40
	global_load_dwordx2 v[24:25], v[24:25], off
	s_nop 0
	global_load_dwordx2 v[26:27], v[26:27], off offset:2048
	s_nop 0
	global_load_dwordx2 v[28:29], v[28:29], off
	s_nop 0
	global_load_dwordx2 v[30:31], v[30:31], off offset:2048
	v_addc_co_u32_e32 v33, vcc, 0, v41, vcc
	v_add_co_u32_e32 v34, vcc, 0x47000, v40
	s_nop 1
	v_addc_co_u32_e32 v35, vcc, 0, v41, vcc
	v_add_co_u32_e32 v36, vcc, 0x4d000, v40
	s_nop 1
	v_addc_co_u32_e32 v37, vcc, 0, v41, vcc
	v_add_co_u32_e32 v38, vcc, 0x52000, v40
	s_nop 1
	v_addc_co_u32_e32 v39, vcc, 0, v41, vcc
	v_add_co_u32_e32 v42, vcc, 0x58000, v40
	global_load_dwordx2 v[32:33], v[32:33], off
	s_nop 0
	global_load_dwordx2 v[34:35], v[34:35], off offset:2048
	s_nop 0
	global_load_dwordx2 v[36:37], v[36:37], off
	s_nop 0
	global_load_dwordx2 v[38:39], v[38:39], off offset:2048
	v_addc_co_u32_e32 v43, vcc, 0, v41, vcc
	v_add_co_u32_e32 v46, vcc, 0x5d000, v40
	s_waitcnt vmcnt(26)
	s_nop 0
	v_addc_co_u32_e32 v47, vcc, 0, v41, vcc
	global_load_dwordx2 v[40:41], v[42:43], off
	s_nop 0
	global_load_dwordx2 v[42:43], v[46:47], off offset:2048
	v_lshl_add_u64 v[46:47], s[14:15], 0, v[44:45]
	global_load_dwordx2 v[44:45], v[46:47], off
	s_nop 0
	global_load_dwordx2 v[46:47], v[50:51], off
	s_andn2_b64 vcc, exec, s[76:77]
	s_cbranch_vccnz .LBB0_1274
	v_readlane_b32 s4, v232, 29
	v_readlane_b32 s5, v232, 30
	s_nop 1
	v_lshl_add_u64 v[50:51], v[48:49], 0, s[4:5]
	v_add_co_u32_e32 v54, vcc, 0x2000, v50
	s_nop 1
	v_addc_co_u32_e32 v55, vcc, 0, v51, vcc
	global_load_dword v53, v[50:51], off nt
	global_load_dword v57, v[54:55], off offset:3072 nt

.LBB0_1300:
	s_waitcnt vmcnt(8)
	v_mov_b32_e32 v102, v97
	v_mov_b32_e32 v104, v113
	v_mov_b32_e32 v105, v115
	v_mov_b32_e32 v107, v130
	v_mov_b32_e32 v108, v136
	v_mov_b32_e32 v109, v139
	v_mov_b32_e32 v110, v141
	v_mov_b32_e32 v111, v140
	v_mov_b32_e32 v116, v2
	v_mov_b32_e32 v117, v112
	v_mov_b32_e32 v118, v99
	v_mov_b32_e32 v119, v127
	v_mov_b32_e32 v120, v126
	v_mov_b32_e32 v121, v137
	v_mov_b32_e32 v122, v138
	s_cmp_eq_u32 s25, 28
	v_mov_b32_e32 v125, v142
	s_cbranch_scc1 .LBB0_1299
	s_add_i32 s30, s22, s25
	s_add_i32 s30, s30, 5
	s_cmp_gt_u32 s30, 63
	s_cselect_b64 s[4:5], -1, 0
	s_cmp_lt_u32 s30, 64
	s_cselect_b64 s[28:29], -1, 0
	s_or_b64 vcc, s[66:67], s[4:5]
	v_mov_b32_e32 v7, 0
	s_and_b64 vcc, exec, vcc
	v_mov_b32_e32 v5, 0
	v_mov_b32_e32 v96, 0
	s_cbranch_vccnz .LBB0_1303
	s_add_i32 s31, s23, s25
	s_addk_i32 s31, 0xfc5
	s_mul_i32 s98, s31, 0x5800
	s_add_u32 s98, s98, s10
	s_addc_u32 s99, s11, 0
	global_load_dword v5, v162, s[98:99] nt
	global_load_dword v96, v163, s[98:99] nt
.LBB0_1303:
	s_andn2_b64 vcc, exec, s[28:29]
	v_mov_b32_e32 v98, 0
	v_mov_b32_e32 v101, 0
	v_mov_b32_e32 v100, 0
	s_cbranch_vccnz .LBB0_1305
	s_add_i32 s31, s23, s25
	s_add_i32 s28, s31, 0x1005
	s_addk_i32 s31, 0x1045
	s_mul_i32 s98, s28, 0x5800
	s_add_u32 s98, s98, s10
	s_addc_u32 s99, s11, 0
	s_mul_i32 s100, s31, 0x5800
	s_add_u32 s100, s100, s10
	s_addc_u32 s101, s11, 0
	global_load_dword v98, v162, s[98:99] nt
	global_load_dword v100, v163, s[98:99] nt
	global_load_dword v7, v162, s[100:101] nt
	global_load_dword v101, v163, s[100:101] nt
.LBB0_1305:
	s_or_b64 s[4:5], s[70:71], s[4:5]
	v_mov_b32_e32 v103, 0
	s_and_b64 vcc, exec, s[4:5]
	v_mov_b32_e32 v106, 0
	v_mov_b32_e32 v114, 0
	s_cbranch_vccnz .LBB0_1307
	s_add_i32 s4, s23, s25
	s_addk_i32 s4, 0x1085
	s_mul_i32 s98, s4, 0x5800
	s_add_u32 s98, s98, s10
	s_addc_u32 s99, s11, 0
	global_load_dword v106, v162, s[98:99] nt
	global_load_dword v114, v163, s[98:99] nt
.LBB0_1307:
	s_cmp_gt_u32 s30, 62
	s_cselect_b64 s[4:5], -1, 0
	s_cmp_lt_u32 s30, 63
	s_cselect_b64 s[28:29], -1, 0
	s_or_b64 vcc, s[66:67], s[4:5]
	s_and_b64 vcc, exec, vcc
	v_mov_b32_e32 v123, 0
	s_cbranch_vccnz .LBB0_1309
	s_add_i32 s31, s23, s25
	s_addk_i32 s31, 0xfc6
	s_mul_i32 s98, s31, 0x5800
	s_add_u32 s98, s98, s10
	s_addc_u32 s99, s11, 0
	global_load_dword v103, v162, s[98:99] nt
	global_load_dword v123, v163, s[98:99] nt
.LBB0_1309:
	v_mov_b32_e32 v124, 0
	s_andn2_b64 vcc, exec, s[28:29]
	v_mov_b32_e32 v129, 0
	v_mov_b32_e32 v128, 0
	v_mov_b32_e32 v133, 0
	v_mov_b32_e32 v131, 0
	s_cbranch_vccnz .LBB0_1311
	s_add_i32 s31, s23, s25
	s_add_i32 s28, s31, 0x1006
	s_addk_i32 s31, 0x1046
	s_mul_i32 s98, s28, 0x5800
	s_add_u32 s98, s98, s10
	s_addc_u32 s99, s11, 0
	s_mul_i32 s100, s31, 0x5800
	s_add_u32 s100, s100, s10
	s_addc_u32 s101, s11, 0
	global_load_dword v128, v162, s[98:99] nt
	global_load_dword v131, v163, s[98:99] nt
	global_load_dword v129, v162, s[100:101] nt
	global_load_dword v133, v163, s[100:101] nt
.LBB0_1311:
	s_or_b64 s[4:5], s[70:71], s[4:5]
	s_and_b64 vcc, exec, s[4:5]
	v_mov_b32_e32 v135, 0
	s_cbranch_vccnz .LBB0_1313
	s_add_i32 s4, s23, s25
	s_addk_i32 s4, 0x1086
	s_mul_i32 s98, s4, 0x5800
	s_add_u32 s98, s98, s10
	s_addc_u32 s99, s11, 0
	global_load_dword v124, v162, s[98:99] nt
	global_load_dword v135, v163, s[98:99] nt
.LBB0_1313:
	s_cmp_gt_u32 s30, 61
	s_cselect_b64 s[4:5], -1, 0
	s_cmp_lt_u32 s30, 62
	s_cselect_b64 s[28:29], -1, 0
	s_or_b64 vcc, s[66:67], s[4:5]
	v_mov_b32_e32 v99, 0
	s_and_b64 vcc, exec, vcc
	v_mov_b32_e32 v2, 0
	v_mov_b32_e32 v97, 0
	s_cbranch_vccnz .LBB0_1315
	s_add_i32 s31, s23, s25
	s_addk_i32 s31, 0xfc7
	s_mul_i32 s98, s31, 0x5800
	s_add_u32 s98, s98, s10
	s_addc_u32 s99, s11, 0
	global_load_dword v2, v162, s[98:99] nt
	global_load_dword v97, v163, s[98:99] nt
.LBB0_1315:
	s_andn2_b64 vcc, exec, s[28:29]
	v_mov_b32_e32 v112, 0
	v_mov_b32_e32 v115, 0
	v_mov_b32_e32 v113, 0
	s_cbranch_vccnz .LBB0_1317
	s_add_i32 s31, s23, s25
	s_add_i32 s28, s31, 0x1007
	s_addk_i32 s31, 0x1047
	s_mul_i32 s98, s28, 0x5800
	s_add_u32 s98, s98, s10
	s_addc_u32 s99, s11, 0
	s_mul_i32 s100, s31, 0x5800
	s_add_u32 s100, s100, s10
	s_addc_u32 s101, s11, 0
	global_load_dword v112, v162, s[98:99] nt
	global_load_dword v113, v163, s[98:99] nt
	global_load_dword v99, v162, s[100:101] nt
	global_load_dword v115, v163, s[100:101] nt
.LBB0_1317:
	s_or_b64 s[4:5], s[70:71], s[4:5]
	v_mov_b32_e32 v126, 0
	s_and_b64 vcc, exec, s[4:5]
	v_mov_b32_e32 v127, 0
	v_mov_b32_e32 v130, 0
	s_cbranch_vccnz .LBB0_1319
	s_add_i32 s4, s23, s25
	s_addk_i32 s4, 0x1087
	s_mul_i32 s98, s4, 0x5800
	s_add_u32 s98, s98, s10
	s_addc_u32 s99, s11, 0
	global_load_dword v127, v162, s[98:99] nt
	global_load_dword v130, v163, s[98:99] nt
.LBB0_1319:
	s_cmp_gt_u32 s30, 60
	s_cselect_b64 s[4:5], -1, 0
	s_cmp_lt_u32 s30, 61
	s_cselect_b64 s[28:29], -1, 0
	s_or_b64 s[30:31], s[66:67], s[4:5]
	s_and_b64 vcc, exec, s[30:31]
	v_mov_b32_e32 v136, 0
	s_cbranch_vccnz .LBB0_1321
	s_add_i32 s30, s23, s25
	s_addk_i32 s30, 0xfc8
	s_mul_i32 s98, s30, 0x5800
	s_add_u32 s98, s98, s10
	s_addc_u32 s99, s11, 0
	global_load_dword v126, v162, s[98:99] nt
	global_load_dword v136, v163, s[98:99] nt
.LBB0_1321:
	v_mov_b32_e32 v140, 0
	s_andn2_b64 vcc, exec, s[28:29]
	v_mov_b32_e32 v138, 0
	v_mov_b32_e32 v137, 0
	v_mov_b32_e32 v141, 0
	v_mov_b32_e32 v139, 0
	s_cbranch_vccnz .LBB0_1323
	s_add_i32 s30, s23, s25
	s_add_i32 s28, s30, 0x1008
	s_addk_i32 s30, 0x1048
	s_mul_i32 s98, s28, 0x5800
	s_add_u32 s98, s98, s10
	s_addc_u32 s99, s11, 0
	s_mul_i32 s100, s30, 0x5800
	s_add_u32 s100, s100, s10
	s_addc_u32 s101, s11, 0
	global_load_dword v137, v162, s[98:99] nt
	global_load_dword v139, v163, s[98:99] nt
	global_load_dword v138, v162, s[100:101] nt
	global_load_dword v141, v163, s[100:101] nt
.LBB0_1323:
	s_or_b64 s[4:5], s[70:71], s[4:5]
	s_and_b64 vcc, exec, s[4:5]
	v_mov_b32_e32 v142, 0
	s_cbranch_vccnz .LBB0_1299
	s_add_i32 s4, s23, s25
	s_addk_i32 s4, 0x1088
	s_mul_i32 s98, s4, 0x5800
	s_add_u32 s98, s98, s10
	s_addc_u32 s99, s11, 0
	global_load_dword v142, v162, s[98:99] nt
	global_load_dword v140, v163, s[98:99] nt
	s_branch .LBB0_1299

.LBB0_2493:
	s_movk_i32 s4, 0x2bf
	v_cmp_lt_i32_e32 vcc, s4, v95
	v_add_lshl_u32 v48, v95, s22, 1
	s_and_saveexec_b64 s[4:5], vcc
	s_xor_b64 s[6:7], exec, s[4:5]
	s_cbranch_execz .LBB0_2508
	v_add_u32_e32 v2, 0xfffffa80, v48
	v_readlane_b32 s4, v232, 17
	v_lshlrev_b64 v[20:21], 2, v[2:3]
	v_readlane_b32 s5, v232, 18
	v_lshl_add_u64 v[22:23], s[14:15], 0, v[20:21]
	v_lshl_add_u64 v[24:25], s[26:27], 0, v[20:21]
	v_lshl_add_u64 v[8:9], s[4:5], 0, v[20:21]
	v_readlane_b32 s4, v232, 19
	v_add_co_u32_e32 v10, vcc, 0x5000, v8
	v_readlane_b32 s5, v232, 20
	s_nop 0
	v_addc_co_u32_e32 v11, vcc, 0, v9, vcc
	v_lshl_add_u64 v[12:13], s[4:5], 0, v[20:21]
	v_readlane_b32 s4, v232, 21
	v_add_co_u32_e32 v14, vcc, 0x5000, v12
	v_readlane_b32 s5, v232, 22
	s_nop 0
	v_addc_co_u32_e32 v15, vcc, 0, v13, vcc
	v_lshl_add_u64 v[16:17], s[4:5], 0, v[20:21]
	global_load_dwordx2 v[8:9], v[8:9], off
	s_nop 0
	global_load_dwordx2 v[10:11], v[10:11], off offset:2048
	s_nop 0
	global_load_dwordx2 v[12:13], v[12:13], off
	s_nop 0
	global_load_dwordx2 v[14:15], v[14:15], off offset:2048
	v_add_co_u32_e32 v18, vcc, 0x5000, v16
	s_nop 1
	v_addc_co_u32_e32 v19, vcc, 0, v17, vcc
	global_load_dwordx2 v[16:17], v[16:17], off
	s_nop 0
	global_load_dwordx2 v[18:19], v[18:19], off offset:2048
	s_nop 0
	global_load_dwordx2 v[20:21], v[22:23], off
	s_nop 0
	global_load_dwordx2 v[22:23], v[24:25], off
	s_andn2_b64 vcc, exec, s[30:31]
	v_lshlrev_b32_e32 v160, 1, v2
	v_add_u32_e32 v161, 0x2c00, v160
	v_lshl_add_u64 v[24:25], v[2:3], 1, s[10:11]
	s_cbranch_vccnz .LBB0_2496
	v_readlane_b32 s4, v232, 27
	v_readlane_b32 s5, v232, 28
	s_nop 1
	v_lshl_add_u64 v[26:27], v[24:25], 0, s[4:5]
	v_add_co_u32_e32 v28, vcc, 0x2000, v26
	s_nop 1
	v_addc_co_u32_e32 v29, vcc, 0, v27, vcc
	global_load_dword v30, v[26:27], off nt
	global_load_dword v31, v[28:29], off offset:3072 nt
	s_branch .LBB0_2497

.LBB0_2499:
	s_waitcnt vmcnt(8)
	v_mov_b32_e32 v51, v47
	v_mov_b32_e32 v52, v61
	v_mov_b32_e32 v53, v66
	v_mov_b32_e32 v54, v63
	v_mov_b32_e32 v58, v2
	v_mov_b32_e32 v59, v57
	v_mov_b32_e32 v60, v65
	s_cmp_eq_u32 s4, 28
	v_mov_b32_e32 v62, v67
	s_cbranch_scc1 .LBB0_2498
	v_lshl_add_u64 v[28:29], s[8:9], 0, v[26:27]
	v_add_co_u32_e32 v46, vcc, 0x15933000, v28
	s_add_i32 s5, s12, s4
	s_nop 0
	v_addc_co_u32_e32 v47, vcc, 0, v29, vcc
	v_add_co_u32_e32 v48, vcc, 0x15936000, v28
	s_add_i32 s5, s5, 5
	s_nop 0
	v_addc_co_u32_e32 v49, vcc, 0, v29, vcc
	global_load_dword v5, v[46:47], off offset:2048 nt
	global_load_dword v7, v[48:49], off offset:1024 nt
	v_mov_b32_e32 v46, 0
	s_cmpk_gt_u32 s5, 0xdf
	v_mov_b32_e32 v49, 0
	v_mov_b32_e32 v50, 0
	s_cbranch_scc1 .LBB0_2502
	s_add_i32 s23, s13, s4
	s_add_i32 s23, s23, 37
	s_mul_i32 s98, s23, 0x5800
	s_add_u32 s98, s98, s10
	s_addc_u32 s99, s11, 0
	global_load_dword v49, v160, s[98:99] nt
	s_nop 0
	global_load_dword v50, v161, s[98:99] nt
.LBB0_2502:
	v_add_co_u32_e32 v56, vcc, 0x15939000, v28
	s_cmpk_gt_u32 s5, 0xde
	s_nop 0
	v_addc_co_u32_e32 v57, vcc, 0, v29, vcc
	v_add_co_u32_e32 v64, vcc, 0x1593b000, v28
	s_nop 1
	v_addc_co_u32_e32 v65, vcc, 0, v29, vcc
	global_load_dword v55, v[56:57], off nt
	s_nop 0
	global_load_dword v56, v[64:65], off offset:3072 nt
	v_mov_b32_e32 v64, 0
	s_cbranch_scc1 .LBB0_2504
	s_add_i32 s23, s13, s4
	s_add_i32 s23, s23, 38
	s_mul_i32 s98, s23, 0x5800
	s_add_u32 s98, s98, s10
	s_addc_u32 s99, s11, 0
	global_load_dword v46, v160, s[98:99] nt
	s_nop 0
	global_load_dword v64, v161, s[98:99] nt
.LBB0_2504:
	v_add_co_u32_e32 v66, vcc, 0x1593e000, v28
	v_mov_b32_e32 v63, 0
	s_nop 0
	v_addc_co_u32_e32 v67, vcc, 0, v29, vcc
	v_add_co_u32_e32 v68, vcc, 0x15941000, v28
	s_cmpk_gt_u32 s5, 0xdd
	s_nop 0
	v_addc_co_u32_e32 v69, vcc, 0, v29, vcc
	global_load_dword v2, v[66:67], off offset:2048 nt
	global_load_dword v47, v[68:69], off offset:1024 nt
	v_mov_b32_e32 v57, 0
	v_mov_b32_e32 v61, 0
	s_cbranch_scc1 .LBB0_2506
	s_add_i32 s23, s13, s4
	s_add_i32 s23, s23, 39
	s_mul_i32 s98, s23, 0x5800
	s_add_u32 s98, s98, s10
	s_addc_u32 s99, s11, 0
	global_load_dword v57, v160, s[98:99] nt
	global_load_dword v61, v161, s[98:99] nt
.LBB0_2506:
	v_add_co_u32_e32 v66, vcc, 0x15944000, v28
	s_cmpk_gt_u32 s5, 0xdc
	s_nop 0
	v_addc_co_u32_e32 v67, vcc, 0, v29, vcc
	v_add_co_u32_e32 v28, vcc, 0x15946000, v28
	s_nop 1
	v_addc_co_u32_e32 v29, vcc, 0, v29, vcc
	global_load_dword v65, v[66:67], off nt
	s_nop 0
	global_load_dword v66, v[28:29], off offset:3072 nt
	v_mov_b32_e32 v67, 0
	s_cbranch_scc1 .LBB0_2498
	s_add_i32 s5, s13, s4
	s_add_i32 s5, s5, 40
	s_mul_i32 s98, s5, 0x5800
	s_add_u32 s98, s98, s10
	s_addc_u32 s99, s11, 0
	global_load_dword v67, v160, s[98:99] nt
	global_load_dword v63, v161, s[98:99] nt
	s_branch .LBB0_2498
.LBB0_2508:
	s_andn2_saveexec_b64 s[16:17], s[6:7]
	s_cbranch_execz .LBB0_2492
	v_ashrrev_i32_e32 v49, 31, v48
	v_readlane_b32 s4, v232, 25
	v_lshlrev_b64 v[44:45], 2, v[48:49]
	v_readlane_b32 s5, v232, 26
	v_lshl_add_u64 v[50:51], s[26:27], 0, v[44:45]
	v_lshlrev_b32_e32 v162, 1, v48
	v_add_u32_e32 v163, 0x2c00, v162
	v_lshl_add_u64 v[48:49], v[48:49], 1, s[10:11]
	v_lshl_add_u64 v[40:41], s[4:5], 0, v[44:45]
	v_add_co_u32_e32 v10, vcc, 0x5000, v40
	v_mov_b32_e32 v52, 0
	s_nop 0
	v_addc_co_u32_e32 v11, vcc, 0, v41, vcc
	v_add_co_u32_e32 v12, vcc, 0xb000, v40
	v_mov_b32_e32 v53, 0
	s_nop 0
	v_addc_co_u32_e32 v13, vcc, 0, v41, vcc
	v_add_co_u32_e32 v14, vcc, 0x10000, v40
	s_waitcnt vmcnt(11)
	v_mov_b32_e32 v57, 0
	v_addc_co_u32_e32 v15, vcc, 0, v41, vcc
	v_add_co_u32_e32 v16, vcc, 0x16000, v40
	global_load_dwordx2 v[8:9], v[40:41], off
	s_nop 0
	global_load_dwordx2 v[10:11], v[10:11], off offset:2048
	s_nop 0
	global_load_dwordx2 v[12:13], v[12:13], off
	s_nop 0
	global_load_dwordx2 v[14:15], v[14:15], off offset:2048
	v_addc_co_u32_e32 v17, vcc, 0, v41, vcc
	v_add_co_u32_e32 v18, vcc, 0x1b000, v40
	s_nop 1
	v_addc_co_u32_e32 v19, vcc, 0, v41, vcc
	v_add_co_u32_e32 v20, vcc, 0x21000, v40
	s_nop 1
	v_addc_co_u32_e32 v21, vcc, 0, v41, vcc
	v_add_co_u32_e32 v22, vcc, 0x26000, v40
	s_nop 1
	v_addc_co_u32_e32 v23, vcc, 0, v41, vcc
	v_add_co_u32_e32 v24, vcc, 0x2c000, v40
	global_load_dwordx2 v[16:17], v[16:17], off
	s_nop 0
	global_load_dwordx2 v[18:19], v[18:19], off offset:2048
	s_nop 0
	global_load_dwordx2 v[20:21], v[20:21], off
	s_nop 0
	global_load_dwordx2 v[22:23], v[22:23], off offset:2048
	v_addc_co_u32_e32 v25, vcc, 0, v41, vcc
	v_add_co_u32_e32 v26, vcc, 0x31000, v40
	s_nop 1
	v_addc_co_u32_e32 v27, vcc, 0, v41, vcc
	v_add_co_u32_e32 v28, vcc, 0x37000, v40
	s_nop 1
	v_addc_co_u32_e32 v29, vcc, 0, v41, vcc
	v_add_co_u32_e32 v30, vcc, 0x3c000, v40
	s_nop 1
	v_addc_co_u32_e32 v31, vcc, 0, v41, vcc
	v_add_co_u32_e32 v32, vcc, 0x42000, v40
	global_load_dwordx2 v[24:25], v[24:25], off
	s_nop 0
	global_load_dwordx2 v[26:27], v[26:27], off offset:2048
	s_nop 0
	global_load_dwordx2 v[28:29], v[28:29], off
	s_nop 0
	global_load_dwordx2 v[30:31], v[30:31], off offset:2048
	v_addc_co_u32_e32 v33, vcc, 0, v41, vcc
	v_add_co_u32_e32 v34, vcc, 0x47000, v40
	s_nop 1
	v_addc_co_u32_e32 v35, vcc, 0, v41, vcc
	v_add_co_u32_e32 v36, vcc, 0x4d000, v40
	s_nop 1
	v_addc_co_u32_e32 v37, vcc, 0, v41, vcc
	v_add_co_u32_e32 v38, vcc, 0x52000, v40
	s_nop 1
	v_addc_co_u32_e32 v39, vcc, 0, v41, vcc
	v_add_co_u32_e32 v42, vcc, 0x58000, v40
	global_load_dwordx2 v[32:33], v[32:33], off
	s_nop 0
	global_load_dwordx2 v[34:35], v[34:35], off offset:2048
	s_nop 0
	global_load_dwordx2 v[36:37], v[36:37], off
	s_nop 0
	global_load_dwordx2 v[38:39], v[38:39], off offset:2048
	v_addc_co_u32_e32 v43, vcc, 0, v41, vcc
	v_add_co_u32_e32 v46, vcc, 0x5d000, v40
	s_waitcnt vmcnt(26)
	s_nop 0
	v_addc_co_u32_e32 v47, vcc, 0, v41, vcc
	global_load_dwordx2 v[40:41], v[42:43], off
	s_nop 0
	global_load_dwordx2 v[42:43], v[46:47], off offset:2048
	v_lshl_add_u64 v[46:47], s[14:15], 0, v[44:45]
	global_load_dwordx2 v[44:45], v[46:47], off
	s_nop 0
	global_load_dwordx2 v[46:47], v[50:51], off
	s_andn2_b64 vcc, exec, s[76:77]
	s_cbranch_vccnz .LBB0_2511
	v_readlane_b32 s4, v232, 29
	v_readlane_b32 s5, v232, 30
	s_nop 1
	v_lshl_add_u64 v[50:51], v[48:49], 0, s[4:5]
	v_add_co_u32_e32 v54, vcc, 0x2000, v50
	s_nop 1
	v_addc_co_u32_e32 v55, vcc, 0, v51, vcc
	global_load_dword v53, v[50:51], off nt
	global_load_dword v57, v[54:55], off offset:3072 nt

.LBB0_2537:
	s_waitcnt vmcnt(8)
	v_mov_b32_e32 v102, v97
	v_mov_b32_e32 v104, v113
	v_mov_b32_e32 v105, v115
	v_mov_b32_e32 v107, v130
	v_mov_b32_e32 v108, v136
	v_mov_b32_e32 v109, v139
	v_mov_b32_e32 v110, v141
	v_mov_b32_e32 v111, v140
	v_mov_b32_e32 v116, v2
	v_mov_b32_e32 v117, v112
	v_mov_b32_e32 v118, v99
	v_mov_b32_e32 v119, v127
	v_mov_b32_e32 v120, v126
	v_mov_b32_e32 v121, v137
	v_mov_b32_e32 v122, v138
	s_cmp_eq_u32 s23, 28
	v_mov_b32_e32 v125, v142
	s_cbranch_scc1 .LBB0_2536
	s_add_i32 s24, s18, s23
	s_add_i32 s24, s24, 5
	s_cmp_gt_u32 s24, 63
	s_cselect_b64 s[4:5], -1, 0
	s_cmp_lt_u32 s24, 64
	s_cselect_b64 s[28:29], -1, 0
	s_or_b64 vcc, s[66:67], s[4:5]
	v_mov_b32_e32 v7, 0
	s_and_b64 vcc, exec, vcc
	v_mov_b32_e32 v5, 0
	v_mov_b32_e32 v96, 0
	s_cbranch_vccnz .LBB0_2540
	s_add_i32 s25, s19, s23
	s_addk_i32 s25, 0xfc5
	s_mul_i32 s98, s25, 0x5800
	s_add_u32 s98, s98, s10
	s_addc_u32 s99, s11, 0
	global_load_dword v5, v162, s[98:99] nt
	global_load_dword v96, v163, s[98:99] nt
.LBB0_2540:
	s_andn2_b64 vcc, exec, s[28:29]
	v_mov_b32_e32 v98, 0
	v_mov_b32_e32 v101, 0
	v_mov_b32_e32 v100, 0
	s_cbranch_vccnz .LBB0_2542
	s_add_i32 s25, s19, s23
	s_add_i32 s28, s25, 0x1005
	s_addk_i32 s25, 0x1045
	s_mul_i32 s98, s28, 0x5800
	s_add_u32 s98, s98, s10
	s_addc_u32 s99, s11, 0
	s_mul_i32 s100, s25, 0x5800
	s_add_u32 s100, s100, s10
	s_addc_u32 s101, s11, 0
	global_load_dword v98, v162, s[98:99] nt
	global_load_dword v100, v163, s[98:99] nt
	global_load_dword v7, v162, s[100:101] nt
	global_load_dword v101, v163, s[100:101] nt
.LBB0_2542:
	s_or_b64 s[4:5], s[70:71], s[4:5]
	v_mov_b32_e32 v103, 0
	s_and_b64 vcc, exec, s[4:5]
	v_mov_b32_e32 v106, 0
	v_mov_b32_e32 v114, 0
	s_cbranch_vccnz .LBB0_2544
	s_add_i32 s4, s19, s23
	s_addk_i32 s4, 0x1085
	s_mul_i32 s98, s4, 0x5800
	s_add_u32 s98, s98, s10
	s_addc_u32 s99, s11, 0
	global_load_dword v106, v162, s[98:99] nt
	global_load_dword v114, v163, s[98:99] nt
.LBB0_2544:
	s_cmp_gt_u32 s24, 62
	s_cselect_b64 s[4:5], -1, 0
	s_cmp_lt_u32 s24, 63
	s_cselect_b64 s[28:29], -1, 0
	s_or_b64 vcc, s[66:67], s[4:5]
	s_and_b64 vcc, exec, vcc
	v_mov_b32_e32 v123, 0
	s_cbranch_vccnz .LBB0_2546
	s_add_i32 s25, s19, s23
	s_addk_i32 s25, 0xfc6
	s_mul_i32 s98, s25, 0x5800
	s_add_u32 s98, s98, s10
	s_addc_u32 s99, s11, 0
	global_load_dword v103, v162, s[98:99] nt
	global_load_dword v123, v163, s[98:99] nt
.LBB0_2546:
	v_mov_b32_e32 v124, 0
	s_andn2_b64 vcc, exec, s[28:29]
	v_mov_b32_e32 v129, 0
	v_mov_b32_e32 v128, 0
	v_mov_b32_e32 v133, 0
	v_mov_b32_e32 v131, 0
	s_cbranch_vccnz .LBB0_2548
	s_add_i32 s25, s19, s23
	s_add_i32 s28, s25, 0x1006
	s_addk_i32 s25, 0x1046
	s_mul_i32 s98, s28, 0x5800
	s_add_u32 s98, s98, s10
	s_addc_u32 s99, s11, 0
	s_mul_i32 s100, s25, 0x5800
	s_add_u32 s100, s100, s10
	s_addc_u32 s101, s11, 0
	global_load_dword v128, v162, s[98:99] nt
	global_load_dword v131, v163, s[98:99] nt
	global_load_dword v129, v162, s[100:101] nt
	global_load_dword v133, v163, s[100:101] nt
.LBB0_2548:
	s_or_b64 s[4:5], s[70:71], s[4:5]
	s_and_b64 vcc, exec, s[4:5]
	v_mov_b32_e32 v135, 0
	s_cbranch_vccnz .LBB0_2550
	s_add_i32 s4, s19, s23
	s_addk_i32 s4, 0x1086
	s_mul_i32 s98, s4, 0x5800
	s_add_u32 s98, s98, s10
	s_addc_u32 s99, s11, 0
	global_load_dword v124, v162, s[98:99] nt
	global_load_dword v135, v163, s[98:99] nt
.LBB0_2550:
	s_cmp_gt_u32 s24, 61
	s_cselect_b64 s[4:5], -1, 0
	s_cmp_lt_u32 s24, 62
	s_cselect_b64 s[28:29], -1, 0
	s_or_b64 vcc, s[66:67], s[4:5]
	v_mov_b32_e32 v99, 0
	s_and_b64 vcc, exec, vcc
	v_mov_b32_e32 v2, 0
	v_mov_b32_e32 v97, 0
	s_cbranch_vccnz .LBB0_2552
	s_add_i32 s25, s19, s23
	s_addk_i32 s25, 0xfc7
	s_mul_i32 s98, s25, 0x5800
	s_add_u32 s98, s98, s10
	s_addc_u32 s99, s11, 0
	global_load_dword v2, v162, s[98:99] nt
	global_load_dword v97, v163, s[98:99] nt
.LBB0_2552:
	s_andn2_b64 vcc, exec, s[28:29]
	v_mov_b32_e32 v112, 0
	v_mov_b32_e32 v115, 0
	v_mov_b32_e32 v113, 0
	s_cbranch_vccnz .LBB0_2554
	s_add_i32 s25, s19, s23
	s_add_i32 s28, s25, 0x1007
	s_addk_i32 s25, 0x1047
	s_mul_i32 s98, s28, 0x5800
	s_add_u32 s98, s98, s10
	s_addc_u32 s99, s11, 0
	s_mul_i32 s100, s25, 0x5800
	s_add_u32 s100, s100, s10
	s_addc_u32 s101, s11, 0
	global_load_dword v112, v162, s[98:99] nt
	global_load_dword v113, v163, s[98:99] nt
	global_load_dword v99, v162, s[100:101] nt
	global_load_dword v115, v163, s[100:101] nt
.LBB0_2554:
	s_or_b64 s[4:5], s[70:71], s[4:5]
	v_mov_b32_e32 v126, 0
	s_and_b64 vcc, exec, s[4:5]
	v_mov_b32_e32 v127, 0
	v_mov_b32_e32 v130, 0
	s_cbranch_vccnz .LBB0_2556
	s_add_i32 s4, s19, s23
	s_addk_i32 s4, 0x1087
	s_mul_i32 s98, s4, 0x5800
	s_add_u32 s98, s98, s10
	s_addc_u32 s99, s11, 0
	global_load_dword v127, v162, s[98:99] nt
	global_load_dword v130, v163, s[98:99] nt
.LBB0_2556:
	s_cmp_gt_u32 s24, 60
	s_cselect_b64 s[4:5], -1, 0
	s_cmp_lt_u32 s24, 61
	s_cselect_b64 s[28:29], -1, 0
	s_or_b64 s[24:25], s[66:67], s[4:5]
	s_and_b64 vcc, exec, s[24:25]
	v_mov_b32_e32 v136, 0
	s_cbranch_vccnz .LBB0_2558
	s_add_i32 s24, s19, s23
	s_addk_i32 s24, 0xfc8
	s_mul_i32 s98, s24, 0x5800
	s_add_u32 s98, s98, s10
	s_addc_u32 s99, s11, 0
	global_load_dword v126, v162, s[98:99] nt
	global_load_dword v136, v163, s[98:99] nt
.LBB0_2558:
	v_mov_b32_e32 v140, 0
	s_andn2_b64 vcc, exec, s[28:29]
	v_mov_b32_e32 v138, 0
	v_mov_b32_e32 v137, 0
	v_mov_b32_e32 v141, 0
	v_mov_b32_e32 v139, 0
	s_cbranch_vccnz .LBB0_2560
	s_add_i32 s28, s19, s23
	s_add_i32 s24, s28, 0x1008
	s_addk_i32 s28, 0x1048
	s_mul_i32 s98, s24, 0x5800
	s_add_u32 s98, s98, s10
	s_addc_u32 s99, s11, 0
	s_mul_i32 s100, s28, 0x5800
	s_add_u32 s100, s100, s10
	s_addc_u32 s101, s11, 0
	global_load_dword v137, v162, s[98:99] nt
	global_load_dword v139, v163, s[98:99] nt
	global_load_dword v138, v162, s[100:101] nt
	global_load_dword v141, v163, s[100:101] nt
.LBB0_2560:
	s_or_b64 s[4:5], s[70:71], s[4:5]
	s_and_b64 vcc, exec, s[4:5]
	v_mov_b32_e32 v142, 0
	s_cbranch_vccnz .LBB0_2536
	s_add_i32 s4, s19, s23
	s_addk_i32 s4, 0x1088
	s_mul_i32 s98, s4, 0x5800
	s_add_u32 s98, s98, s10
	s_addc_u32 s99, s11, 0
	global_load_dword v142, v162, s[98:99] nt
	global_load_dword v140, v163, s[98:99] nt
	s_branch .LBB0_2536

	.amdhsa_kernel _Z10fwd_kernel6Params
		.amdhsa_group_segment_fixed_size 0
		.amdhsa_private_segment_fixed_size 0
		.amdhsa_kernarg_size 520
		.amdhsa_user_sgpr_count 2
		.amdhsa_user_sgpr_dispatch_ptr 0
		.amdhsa_user_sgpr_queue_ptr 0
		.amdhsa_user_sgpr_kernarg_segment_ptr 1
		.amdhsa_user_sgpr_dispatch_id 0
		.amdhsa_user_sgpr_kernarg_preload_length 0
		.amdhsa_user_sgpr_kernarg_preload_offset 0
		.amdhsa_user_sgpr_private_segment_size 0
		.amdhsa_uses_dynamic_stack 0
		.amdhsa_enable_private_segment 0
		.amdhsa_system_sgpr_workgroup_id_x 1
		.amdhsa_system_sgpr_workgroup_id_y 0
		.amdhsa_system_sgpr_workgroup_id_z 0
		.amdhsa_system_sgpr_workgroup_info 0
		.amdhsa_system_vgpr_workitem_id 2
		.amdhsa_next_free_vgpr 233
		.amdhsa_next_free_sgpr 102
		.amdhsa_accum_offset 236
		.amdhsa_reserve_vcc 1
		.amdhsa_float_round_mode_32 0
		.amdhsa_float_round_mode_16_64 0
		.amdhsa_float_denorm_mode_32 3
		.amdhsa_float_denorm_mode_16_64 3
		.amdhsa_dx10_clamp 1
		.amdhsa_ieee_mode 1
		.amdhsa_fp16_overflow 0
		.amdhsa_tg_split 0
		.amdhsa_exception_fp_ieee_invalid_op 0
		.amdhsa_exception_fp_denorm_src 0
		.amdhsa_exception_fp_ieee_div_zero 0
		.amdhsa_exception_fp_ieee_overflow 0
		.amdhsa_exception_fp_ieee_underflow 0
		.amdhsa_exception_fp_ieee_inexact 0
		.amdhsa_exception_int_div_zero 0
	.end_amdhsa_kernel

amdhsa.kernels:
  - .agpr_count:     0
    .args:
      - .offset:         0
        .size:           264
        .value_kind:     by_value
      - .offset:         264
        .size:           4
        .value_kind:     hidden_block_count_x
      - .offset:         268
        .size:           4
        .value_kind:     hidden_block_count_y
      - .offset:         272
        .size:           4
        .value_kind:     hidden_block_count_z
      - .offset:         276
        .size:           2
        .value_kind:     hidden_group_size_x
      - .offset:         278
        .size:           2
        .value_kind:     hidden_group_size_y
      - .offset:         280
        .size:           2
        .value_kind:     hidden_group_size_z
      - .offset:         282
        .size:           2
        .value_kind:     hidden_remainder_x
      - .offset:         284
        .size:           2
        .value_kind:     hidden_remainder_y
      - .offset:         286
        .size:           2
        .value_kind:     hidden_remainder_z
      - .offset:         304
        .size:           8
        .value_kind:     hidden_global_offset_x
      - .offset:         312
        .size:           8
        .value_kind:     hidden_global_offset_y
      - .offset:         320
        .size:           8
        .value_kind:     hidden_global_offset_z
      - .offset:         328
        .size:           2
        .value_kind:     hidden_grid_dims
      - .offset:         352
        .size:           8
        .value_kind:     hidden_multigrid_sync_arg
      - .offset:         384
        .size:           4
        .value_kind:     hidden_dynamic_lds_size
    .group_segment_fixed_size: 0
    .kernarg_segment_align: 8
    .kernarg_segment_size: 520
    .language:       OpenCL C
    .language_version:
      - 2
      - 0
    .max_flat_workgroup_size: 512
    .name:           _Z10fwd_kernel6Params
    .private_segment_fixed_size: 0
    .sgpr_count:     108
    .sgpr_spill_count: 105
    .symbol:         _Z10fwd_kernel6Params.kd
    .uniform_work_group_size: 1
    .uses_dynamic_stack: false
    .vgpr_count:     233
    .vgpr_spill_count: 0
    .wavefront_size: 64
